# P7 w_q big-tile epilogue de-serialised: 8 rstd1 loads issued together, per-group vmcnt(0) (store drain) removed
# speedup vs baseline: 1.0019x; 1.0019x over previous
.LBB0_921:
	v_mov_b32_e32 v138, v136
	s_lshl_b32 s21, s22, 8
	s_nop 0
	v_ashrrev_i32_e32 v128, 2, v138
	v_and_b32_e32 v128, 0xffffffc0, v128
	v_and_or_b32 v130, v138, 15, s21
	v_add_u32_e32 v130, v130, v128
	v_ashrrev_i32_e32 v131, 31, v130
	v_lshl_add_u64 v[134:135], v[130:131], 2, s[46:47]
	global_load_dword v128, v[134:135], off
	global_load_dword v170, v[134:135], off offset:64
	global_load_dword v171, v[134:135], off offset:128
	global_load_dword v172, v[134:135], off offset:192
	global_load_dword v173, v[134:135], off offset:512
	global_load_dword v174, v[134:135], off offset:576
	global_load_dword v175, v[134:135], off offset:640
	global_load_dword v176, v[134:135], off offset:704
	v_lshrrev_b32_e32 v138, 1, v138
	v_and_b32_e32 v138, 0x78, v138
	v_lshl_or_b32 v138, s20, 8, v138
	v_ashrrev_i32_e32 v139, 31, v138
	v_lshl_add_u64 v[138:139], v[138:139], 1, s[62:63]
	v_lshlrev_b64 v[140:141], 11, v[130:131]
	v_lshl_add_u64 v[140:141], v[138:139], 0, v[140:141]
	s_waitcnt vmcnt(0)
	v_pk_mul_f32 v[142:143], v[114:115], v[128:129] op_sel_hi:[1,0]
	v_pk_mul_f32 v[114:115], v[112:113], v[128:129] op_sel_hi:[1,0]
	v_pk_mul_f32 v[118:119], v[118:119], v[128:129] op_sel_hi:[1,0]
	v_pk_mul_f32 v[116:117], v[116:117], v[128:129] op_sel_hi:[1,0]
	v_cvt_pk_bf16_f32 v113, v118, v119
	v_cvt_pk_bf16_f32 v114, v114, v115
	v_cvt_pk_bf16_f32 v115, v142, v143
	v_pk_mul_f32 v[126:127], v[126:127], v[128:129] op_sel_hi:[1,0]
	v_cvt_pk_bf16_f32 v112, v116, v117
	v_pk_mul_f32 v[124:125], v[124:125], v[128:129] op_sel_hi:[1,0]
	v_pk_mul_f32 v[122:123], v[122:123], v[128:129] op_sel_hi:[1,0]
	v_pk_mul_f32 v[120:121], v[120:121], v[128:129] op_sel_hi:[1,0]
	v_cvt_pk_bf16_f32 v116, v124, v125
	v_cvt_pk_bf16_f32 v117, v126, v127
	v_cvt_pk_bf16_f32 v119, v122, v123
	s_nop 0
	v_cvt_pk_bf16_f32 v118, v120, v121
	global_store_dwordx4 v[140:141], v[112:115], off
	global_store_dwordx4 v[140:141], v[116:119], off offset:256
	v_mov_b32_e32 v112, v170
	v_or_b32_e32 v114, 16, v130
	v_ashrrev_i32_e32 v115, 31, v114
	v_lshlrev_b64 v[114:115], 11, v[114:115]
	v_lshl_add_u64 v[114:115], v[138:139], 0, v[114:115]
	v_pk_mul_f32 v[116:117], v[98:99], v[112:113] op_sel_hi:[1,0]
	v_pk_mul_f32 v[98:99], v[96:97], v[112:113] op_sel_hi:[1,0]
	v_pk_mul_f32 v[102:103], v[102:103], v[112:113] op_sel_hi:[1,0]
	v_pk_mul_f32 v[100:101], v[100:101], v[112:113] op_sel_hi:[1,0]
	v_cvt_pk_bf16_f32 v97, v102, v103
	v_cvt_pk_bf16_f32 v98, v98, v99
	v_cvt_pk_bf16_f32 v99, v116, v117
	v_pk_mul_f32 v[110:111], v[110:111], v[112:113] op_sel_hi:[1,0]
	v_cvt_pk_bf16_f32 v96, v100, v101
	v_pk_mul_f32 v[108:109], v[108:109], v[112:113] op_sel_hi:[1,0]
	v_pk_mul_f32 v[106:107], v[106:107], v[112:113] op_sel_hi:[1,0]
	v_pk_mul_f32 v[104:105], v[104:105], v[112:113] op_sel_hi:[1,0]
	v_cvt_pk_bf16_f32 v100, v108, v109
	v_cvt_pk_bf16_f32 v101, v110, v111
	v_cvt_pk_bf16_f32 v103, v106, v107
	s_nop 0
	v_cvt_pk_bf16_f32 v102, v104, v105
	global_store_dwordx4 v[114:115], v[96:99], off
	global_store_dwordx4 v[114:115], v[100:103], off offset:256
	v_mov_b32_e32 v96, v171
	v_or_b32_e32 v98, 32, v130
	v_ashrrev_i32_e32 v99, 31, v98
	v_lshlrev_b64 v[98:99], 11, v[98:99]
	v_lshl_add_u64 v[98:99], v[138:139], 0, v[98:99]
	v_pk_mul_f32 v[100:101], v[82:83], v[96:97] op_sel_hi:[1,0]
	v_pk_mul_f32 v[82:83], v[80:81], v[96:97] op_sel_hi:[1,0]
	v_pk_mul_f32 v[86:87], v[86:87], v[96:97] op_sel_hi:[1,0]
	v_pk_mul_f32 v[84:85], v[84:85], v[96:97] op_sel_hi:[1,0]
	v_cvt_pk_bf16_f32 v81, v86, v87
	v_cvt_pk_bf16_f32 v82, v82, v83
	v_cvt_pk_bf16_f32 v83, v100, v101
	v_pk_mul_f32 v[94:95], v[94:95], v[96:97] op_sel_hi:[1,0]
	v_cvt_pk_bf16_f32 v80, v84, v85
	v_pk_mul_f32 v[92:93], v[92:93], v[96:97] op_sel_hi:[1,0]
	v_pk_mul_f32 v[90:91], v[90:91], v[96:97] op_sel_hi:[1,0]
	v_pk_mul_f32 v[88:89], v[88:89], v[96:97] op_sel_hi:[1,0]
	v_cvt_pk_bf16_f32 v84, v92, v93
	v_cvt_pk_bf16_f32 v85, v94, v95
	v_cvt_pk_bf16_f32 v87, v90, v91
	s_nop 0
	v_cvt_pk_bf16_f32 v86, v88, v89
	global_store_dwordx4 v[98:99], v[80:83], off
	global_store_dwordx4 v[98:99], v[84:87], off offset:256
	v_mov_b32_e32 v80, v172
	v_or_b32_e32 v82, 48, v130
	v_ashrrev_i32_e32 v83, 31, v82
	v_lshlrev_b64 v[82:83], 11, v[82:83]
	v_lshl_add_u64 v[82:83], v[138:139], 0, v[82:83]
	v_pk_mul_f32 v[84:85], v[66:67], v[80:81] op_sel_hi:[1,0]
	v_pk_mul_f32 v[66:67], v[64:65], v[80:81] op_sel_hi:[1,0]
	v_pk_mul_f32 v[70:71], v[70:71], v[80:81] op_sel_hi:[1,0]
	v_pk_mul_f32 v[68:69], v[68:69], v[80:81] op_sel_hi:[1,0]
	v_cvt_pk_bf16_f32 v65, v70, v71
	v_cvt_pk_bf16_f32 v66, v66, v67
	v_cvt_pk_bf16_f32 v67, v84, v85
	v_pk_mul_f32 v[78:79], v[78:79], v[80:81] op_sel_hi:[1,0]
	v_cvt_pk_bf16_f32 v64, v68, v69
	v_pk_mul_f32 v[76:77], v[76:77], v[80:81] op_sel_hi:[1,0]
	v_pk_mul_f32 v[74:75], v[74:75], v[80:81] op_sel_hi:[1,0]
	v_pk_mul_f32 v[72:73], v[72:73], v[80:81] op_sel_hi:[1,0]
	v_cvt_pk_bf16_f32 v68, v76, v77
	v_cvt_pk_bf16_f32 v69, v78, v79
	v_cvt_pk_bf16_f32 v71, v74, v75
	s_nop 0
	v_cvt_pk_bf16_f32 v70, v72, v73
	global_store_dwordx4 v[82:83], v[64:67], off
	global_store_dwordx4 v[82:83], v[68:71], off offset:256
	v_mov_b32_e32 v64, v173
	v_add_u32_e32 v66, 0x80, v130
	v_ashrrev_i32_e32 v67, 31, v66
	v_lshlrev_b64 v[66:67], 11, v[66:67]
	v_lshl_add_u64 v[66:67], v[138:139], 0, v[66:67]
	v_pk_mul_f32 v[62:63], v[62:63], v[64:65] op_sel_hi:[1,0]
	v_pk_mul_f32 v[60:61], v[60:61], v[64:65] op_sel_hi:[1,0]
	v_pk_mul_f32 v[58:59], v[58:59], v[64:65] op_sel_hi:[1,0]
	v_pk_mul_f32 v[56:57], v[56:57], v[64:65] op_sel_hi:[1,0]
	v_pk_mul_f32 v[54:55], v[54:55], v[64:65] op_sel_hi:[1,0]
	v_pk_mul_f32 v[52:53], v[52:53], v[64:65] op_sel_hi:[1,0]
	v_pk_mul_f32 v[68:69], v[50:51], v[64:65] op_sel_hi:[1,0]
	v_pk_mul_f32 v[64:65], v[48:49], v[64:65] op_sel_hi:[1,0]
	v_cvt_pk_bf16_f32 v48, v60, v61
	v_cvt_pk_bf16_f32 v49, v62, v63
	v_cvt_pk_bf16_f32 v50, v56, v57
	v_cvt_pk_bf16_f32 v51, v58, v59
	v_cvt_pk_bf16_f32 v52, v52, v53
	v_cvt_pk_bf16_f32 v53, v54, v55
	s_nop 0
	v_cvt_pk_bf16_f32 v54, v64, v65
	v_cvt_pk_bf16_f32 v55, v68, v69
	global_store_dwordx4 v[66:67], v[48:51], off
	global_store_dwordx4 v[66:67], v[52:55], off offset:256
	v_mov_b32_e32 v48, v174
	v_add_u32_e32 v50, 0x90, v130
	v_ashrrev_i32_e32 v51, 31, v50
	v_lshlrev_b64 v[50:51], 11, v[50:51]
	v_lshl_add_u64 v[50:51], v[138:139], 0, v[50:51]
	v_pk_mul_f32 v[46:47], v[46:47], v[48:49] op_sel_hi:[1,0]
	v_pk_mul_f32 v[44:45], v[44:45], v[48:49] op_sel_hi:[1,0]
	v_pk_mul_f32 v[42:43], v[42:43], v[48:49] op_sel_hi:[1,0]
	v_pk_mul_f32 v[40:41], v[40:41], v[48:49] op_sel_hi:[1,0]
	v_pk_mul_f32 v[38:39], v[38:39], v[48:49] op_sel_hi:[1,0]
	v_pk_mul_f32 v[36:37], v[36:37], v[48:49] op_sel_hi:[1,0]
	v_pk_mul_f32 v[52:53], v[34:35], v[48:49] op_sel_hi:[1,0]
	v_pk_mul_f32 v[48:49], v[32:33], v[48:49] op_sel_hi:[1,0]
	v_cvt_pk_bf16_f32 v32, v44, v45
	v_cvt_pk_bf16_f32 v33, v46, v47
	v_cvt_pk_bf16_f32 v34, v40, v41
	v_cvt_pk_bf16_f32 v35, v42, v43
	v_cvt_pk_bf16_f32 v36, v36, v37
	v_cvt_pk_bf16_f32 v37, v38, v39
	s_nop 0
	v_cvt_pk_bf16_f32 v38, v48, v49
	v_cvt_pk_bf16_f32 v39, v52, v53
	global_store_dwordx4 v[50:51], v[32:35], off
	global_store_dwordx4 v[50:51], v[36:39], off offset:256
	v_mov_b32_e32 v32, v175
	v_add_u32_e32 v34, 0xa0, v130
	v_ashrrev_i32_e32 v35, 31, v34
	v_lshlrev_b64 v[34:35], 11, v[34:35]
	v_lshl_add_u64 v[34:35], v[138:139], 0, v[34:35]
	v_pk_mul_f32 v[30:31], v[30:31], v[32:33] op_sel_hi:[1,0]
	v_pk_mul_f32 v[28:29], v[28:29], v[32:33] op_sel_hi:[1,0]
	v_pk_mul_f32 v[26:27], v[26:27], v[32:33] op_sel_hi:[1,0]
	v_pk_mul_f32 v[24:25], v[24:25], v[32:33] op_sel_hi:[1,0]
	v_pk_mul_f32 v[22:23], v[22:23], v[32:33] op_sel_hi:[1,0]
	v_pk_mul_f32 v[20:21], v[20:21], v[32:33] op_sel_hi:[1,0]
	v_pk_mul_f32 v[36:37], v[18:19], v[32:33] op_sel_hi:[1,0]
	v_pk_mul_f32 v[32:33], v[16:17], v[32:33] op_sel_hi:[1,0]
	v_cvt_pk_bf16_f32 v16, v28, v29
	v_cvt_pk_bf16_f32 v17, v30, v31
	v_cvt_pk_bf16_f32 v18, v24, v25
	v_cvt_pk_bf16_f32 v19, v26, v27
	v_cvt_pk_bf16_f32 v20, v20, v21
	v_cvt_pk_bf16_f32 v21, v22, v23
	s_nop 0
	v_cvt_pk_bf16_f32 v22, v32, v33
	v_cvt_pk_bf16_f32 v23, v36, v37
	global_store_dwordx4 v[34:35], v[16:19], off
	global_store_dwordx4 v[34:35], v[20:23], off offset:256
	v_mov_b32_e32 v16, v176
	v_add_u32_e32 v18, 0xb0, v130
	v_ashrrev_i32_e32 v19, 31, v18
	v_lshlrev_b64 v[18:19], 11, v[18:19]
	v_lshl_add_u64 v[18:19], v[138:139], 0, v[18:19]
	v_pk_mul_f32 v[14:15], v[14:15], v[16:17] op_sel_hi:[1,0]
	v_pk_mul_f32 v[12:13], v[12:13], v[16:17] op_sel_hi:[1,0]
	v_pk_mul_f32 v[10:11], v[10:11], v[16:17] op_sel_hi:[1,0]
	v_pk_mul_f32 v[8:9], v[8:9], v[16:17] op_sel_hi:[1,0]
	v_pk_mul_f32 v[6:7], v[6:7], v[16:17] op_sel_hi:[1,0]
	v_pk_mul_f32 v[4:5], v[4:5], v[16:17] op_sel_hi:[1,0]
	v_pk_mul_f32 v[20:21], v[2:3], v[16:17] op_sel_hi:[1,0]
	v_pk_mul_f32 v[16:17], v[0:1], v[16:17] op_sel_hi:[1,0]
	v_cvt_pk_bf16_f32 v0, v12, v13
	v_cvt_pk_bf16_f32 v1, v14, v15
	v_cvt_pk_bf16_f32 v2, v8, v9
	v_cvt_pk_bf16_f32 v3, v10, v11
	v_cvt_pk_bf16_f32 v4, v4, v5
	v_cvt_pk_bf16_f32 v5, v6, v7
	s_nop 0
	v_cvt_pk_bf16_f32 v6, v16, v17
	v_cvt_pk_bf16_f32 v7, v20, v21
	global_store_dwordx4 v[18:19], v[0:3], off
	global_store_dwordx4 v[18:19], v[4:7], off offset:256
